# bundle: MLP-up epilogue load hoist + K-loop setprio/wait cleanup + permlane32_swap for softmax row-max exchange + first-barrier census loads pipelined
# baseline (speedup 1.0000x reference)
.LBB0_199:
	v_readlane_b32 s6, v252, 63
	v_readlane_b32 s7, v253, 0
	global_load_dword v5, v0, s[58:59] sc1
	global_load_dword v1, v0, s[60:61] sc1
	s_waitcnt lgkmcnt(0)
	global_load_dword v2, v0, s[62:63] sc1
	global_load_dword v3, v0, s[56:57] sc1
	global_load_dword v4, v0, s[54:55] sc1
	global_load_dword v6, v0, s[6:7] sc1
	v_readlane_b32 s6, v253, 1
	v_readlane_b32 s7, v253, 2
	v_readlane_b32 s8, v254, 36
	s_nop 4
	global_load_dword v7, v0, s[6:7] sc1
	v_readlane_b32 s6, v253, 3
	v_readlane_b32 s7, v253, 4
	s_nop 4
	global_load_dword v8, v0, s[6:7] sc1
	v_readlane_b32 s6, v253, 5
	v_readlane_b32 s7, v253, 6
	s_nop 4
	global_load_dword v9, v0, s[6:7] sc1
	v_readlane_b32 s6, v253, 7
	v_readlane_b32 s7, v253, 8
	s_nop 4
	global_load_dword v10, v0, s[6:7] sc1
	v_readlane_b32 s6, v253, 9
	v_readlane_b32 s7, v253, 10
	s_nop 4
	global_load_dword v11, v0, s[6:7] sc1
	v_readlane_b32 s6, v253, 11
	v_readlane_b32 s7, v253, 12
	s_nop 4
	global_load_dword v12, v0, s[6:7] sc1
	v_readlane_b32 s6, v253, 13
	v_readlane_b32 s7, v253, 14
	s_nop 4
	global_load_dword v13, v0, s[6:7] sc1
	v_readlane_b32 s6, v253, 15
	v_readlane_b32 s7, v253, 16
	s_nop 4
	global_load_dword v14, v0, s[6:7] sc1
	v_readlane_b32 s6, v253, 17
	v_readlane_b32 s7, v253, 18
	s_nop 4
	global_load_dword v15, v0, s[6:7] sc1
	v_readlane_b32 s6, v253, 19
	v_readlane_b32 s7, v253, 20
	s_nop 4
	global_load_dword v16, v0, s[6:7] sc1
	s_mov_b64 s[6:7], -1
	s_waitcnt vmcnt(0)
	v_add_u32_e32 v17, v1, v5
	v_add_u32_e32 v17, v17, v2
	v_add_u32_e32 v17, v17, v3
	v_add_u32_e32 v17, v17, v4
	v_add_u32_e32 v17, v17, v6
	v_add_u32_e32 v17, v17, v7
	v_add_u32_e32 v17, v17, v8
	v_add_u32_e32 v17, v17, v9
	v_add_u32_e32 v17, v17, v10
	v_add_u32_e32 v17, v17, v11
	v_add_u32_e32 v17, v17, v12
	v_add_u32_e32 v17, v17, v13
	v_add_u32_e32 v17, v17, v14
	v_add_u32_e32 v17, v17, v15
	v_add_u32_e32 v17, v17, v16
	v_cmp_eq_u32_e32 vcc, s8, v17
	s_mov_b64 s[8:9], -1
	s_cbranch_vccnz .LBB0_198
	s_and_b32 s6, s35, 0xff
	s_cmp_eq_u32 s6, 0
	s_mov_b64 s[6:7], -1
	s_mov_b64 s[16:17], -1
	s_sleep 1
	s_cbranch_scc0 .LBB0_203
	global_load_dword v17, v0, s[84:85] sc1
	s_waitcnt vmcnt(0)
	v_cmp_eq_u32_e32 vcc, 0, v17
	s_cbranch_vccnz .LBB0_205
	s_mov_b64 s[16:17], 0

.LBB0_331:
	v_add_f32_e32 v7, v7, v6
	v_mov_b32_e32 v8, v7
	s_nop 1
	v_permlane32_swap_b32_e32 v7, v8
	v_max_f32_e32 v8, v8, v8
	v_max_f32_e32 v7, v7, v8
	v_add_f32_e32 v8, 0x42000000, v246
	v_cmp_gt_f32_e32 vcc, v7, v8
	s_cbranch_vccz .LBB0_333
	v_max_f32_e32 v7, v7, v7
	v_max_f32_e32 v8, v246, v246
	v_max_f32_e32 v7, v8, v7
	v_sub_f32_e32 v8, v246, v7
	v_exp_f32_e32 v8, v8
	v_mov_b32_e32 v246, v7
	v_mul_f32_e32 v64, v8, v64
	v_mul_f32_e32 v65, v8, v65
	v_mul_f32_e32 v66, v8, v66
	v_mul_f32_e32 v67, v8, v67
	v_mul_f32_e32 v68, v8, v68
	v_mul_f32_e32 v69, v8, v69
	v_mul_f32_e32 v70, v8, v70
	v_mul_f32_e32 v71, v8, v71
	v_mul_f32_e32 v72, v8, v72
	v_mul_f32_e32 v73, v8, v73
	v_mul_f32_e32 v74, v8, v74
	v_mul_f32_e32 v75, v8, v75
	v_mul_f32_e32 v76, v8, v76
	v_mul_f32_e32 v77, v8, v77
	v_mul_f32_e32 v78, v8, v78
	v_mul_f32_e32 v79, v8, v79
	v_mul_f32_e32 v48, v8, v48
	v_mul_f32_e32 v49, v8, v49
	v_mul_f32_e32 v50, v8, v50
	v_mul_f32_e32 v51, v8, v51
	v_mul_f32_e32 v52, v8, v52
	v_mul_f32_e32 v53, v8, v53
	v_mul_f32_e32 v54, v8, v54
	v_mul_f32_e32 v55, v8, v55
	v_mul_f32_e32 v56, v8, v56
	v_mul_f32_e32 v57, v8, v57
	v_mul_f32_e32 v58, v8, v58
	v_mul_f32_e32 v59, v8, v59
	v_mul_f32_e32 v60, v8, v60
	v_mul_f32_e32 v61, v8, v61
	v_mul_f32_e32 v62, v8, v62
	v_mul_f32_e32 v63, v8, v63
	v_mul_f32_e32 v32, v8, v32
	v_mul_f32_e32 v33, v8, v33
	v_mul_f32_e32 v34, v8, v34
	v_mul_f32_e32 v35, v8, v35
	v_mul_f32_e32 v36, v8, v36
	v_mul_f32_e32 v37, v8, v37
	v_mul_f32_e32 v38, v8, v38
	v_mul_f32_e32 v39, v8, v39
	v_mul_f32_e32 v40, v8, v40
	v_mul_f32_e32 v41, v8, v41
	v_mul_f32_e32 v42, v8, v42
	v_mul_f32_e32 v43, v8, v43
	v_mul_f32_e32 v44, v8, v44
	v_mul_f32_e32 v45, v8, v45
	v_mul_f32_e32 v46, v8, v46
	v_mul_f32_e32 v47, v8, v47
	v_mul_f32_e32 v16, v8, v16
	v_mul_f32_e32 v17, v8, v17
	v_mul_f32_e32 v18, v8, v18
	v_mul_f32_e32 v19, v8, v19
	v_mul_f32_e32 v20, v8, v20
	v_mul_f32_e32 v21, v8, v21
	v_mul_f32_e32 v22, v8, v22
	v_mul_f32_e32 v23, v8, v23
	v_mul_f32_e32 v24, v8, v24
	v_mul_f32_e32 v25, v8, v25
	v_mul_f32_e32 v26, v8, v26
	v_mul_f32_e32 v27, v8, v27
	v_mul_f32_e32 v28, v8, v28
	v_mul_f32_e32 v29, v8, v29
	v_mul_f32_e32 v30, v8, v30
	v_mul_f32_e32 v31, v8, v31
	v_mul_f32_e32 v245, v245, v8

.LBB0_400:
	v_add_f32_e32 v2, v4, v3
	v_mov_b32_e32 v4, v2
	s_nop 1
	v_permlane32_swap_b32_e32 v2, v4
	v_max_f32_e32 v4, v4, v4
	v_max_f32_e32 v2, v2, v4
	v_add_f32_e32 v4, 0x42000000, v246
	v_cmp_gt_f32_e32 vcc, v2, v4
	s_cbranch_vccz .LBB0_402
	v_max_f32_e32 v2, v2, v2
	v_max_f32_e32 v4, v246, v246
	v_max_f32_e32 v2, v4, v2
	v_sub_f32_e32 v4, v246, v2
	v_exp_f32_e32 v4, v4
	v_mov_b32_e32 v246, v2
	v_mul_f32_e32 v64, v4, v64
	v_mul_f32_e32 v65, v4, v65
	v_mul_f32_e32 v66, v4, v66
	v_mul_f32_e32 v67, v4, v67
	v_mul_f32_e32 v68, v4, v68
	v_mul_f32_e32 v69, v4, v69
	v_mul_f32_e32 v70, v4, v70
	v_mul_f32_e32 v71, v4, v71
	v_mul_f32_e32 v72, v4, v72
	v_mul_f32_e32 v73, v4, v73
	v_mul_f32_e32 v74, v4, v74
	v_mul_f32_e32 v75, v4, v75
	v_mul_f32_e32 v76, v4, v76
	v_mul_f32_e32 v77, v4, v77
	v_mul_f32_e32 v78, v4, v78
	v_mul_f32_e32 v79, v4, v79
	v_mul_f32_e32 v48, v4, v48
	v_mul_f32_e32 v49, v4, v49
	v_mul_f32_e32 v50, v4, v50
	v_mul_f32_e32 v51, v4, v51
	v_mul_f32_e32 v52, v4, v52
	v_mul_f32_e32 v53, v4, v53
	v_mul_f32_e32 v54, v4, v54
	v_mul_f32_e32 v55, v4, v55
	v_mul_f32_e32 v56, v4, v56
	v_mul_f32_e32 v57, v4, v57
	v_mul_f32_e32 v58, v4, v58
	v_mul_f32_e32 v59, v4, v59
	v_mul_f32_e32 v60, v4, v60
	v_mul_f32_e32 v61, v4, v61
	v_mul_f32_e32 v62, v4, v62
	v_mul_f32_e32 v63, v4, v63
	v_mul_f32_e32 v32, v4, v32
	v_mul_f32_e32 v33, v4, v33
	v_mul_f32_e32 v34, v4, v34
	v_mul_f32_e32 v35, v4, v35
	v_mul_f32_e32 v36, v4, v36
	v_mul_f32_e32 v37, v4, v37
	v_mul_f32_e32 v38, v4, v38
	v_mul_f32_e32 v39, v4, v39
	v_mul_f32_e32 v40, v4, v40
	v_mul_f32_e32 v41, v4, v41
	v_mul_f32_e32 v42, v4, v42
	v_mul_f32_e32 v43, v4, v43
	v_mul_f32_e32 v44, v4, v44
	v_mul_f32_e32 v45, v4, v45
	v_mul_f32_e32 v46, v4, v46
	v_mul_f32_e32 v47, v4, v47
	v_mul_f32_e32 v16, v4, v16
	v_mul_f32_e32 v17, v4, v17
	v_mul_f32_e32 v18, v4, v18
	v_mul_f32_e32 v19, v4, v19
	v_mul_f32_e32 v20, v4, v20
	v_mul_f32_e32 v21, v4, v21
	v_mul_f32_e32 v22, v4, v22
	v_mul_f32_e32 v23, v4, v23
	v_mul_f32_e32 v24, v4, v24
	v_mul_f32_e32 v25, v4, v25
	v_mul_f32_e32 v26, v4, v26
	v_mul_f32_e32 v27, v4, v27
	v_mul_f32_e32 v28, v4, v28
	v_mul_f32_e32 v29, v4, v29
	v_mul_f32_e32 v30, v4, v30
	v_mul_f32_e32 v31, v4, v31
	v_mul_f32_e32 v245, v245, v4

.LBB0_464:
	v_max3_f32 v49, v193, s52, v34
	v_max3_f32 v49, v49, v35, v36
	v_max3_f32 v49, v49, v37, v38
	v_max3_f32 v49, v49, v39, v40
	v_max3_f32 v49, v49, v41, v42
	v_max3_f32 v49, v49, v43, v44
	v_max3_f32 v49, v49, v45, v46
	v_max3_f32 v49, v49, v47, v48
	v_mov_b32_e32 v170, v49
	s_nop 1
	v_permlane32_swap_b32_e32 v49, v170
	v_max_f32_e32 v170, v170, v170
	v_max_f32_e32 v49, v49, v170
	v_add_f32_e32 v170, 0x42000000, v162
	v_cmp_gt_f32_e32 vcc, v49, v170
	s_cbranch_vccz .LBB0_466
	v_max_f32_e32 v49, v49, v49
	v_max_f32_e32 v170, v162, v162
	v_max_f32_e32 v49, v170, v49
	v_sub_f32_e32 v162, v162, v49
	v_exp_f32_e32 v162, v162
	s_nop 0
	v_mul_f32_e32 v2, v2, v162
	v_mul_f32_e32 v3, v3, v162
	v_mul_f32_e32 v4, v4, v162
	v_mul_f32_e32 v5, v5, v162
	v_mul_f32_e32 v6, v6, v162
	v_mul_f32_e32 v7, v7, v162
	v_mul_f32_e32 v8, v8, v162
	v_mul_f32_e32 v9, v9, v162
	v_mul_f32_e32 v10, v10, v162
	v_mul_f32_e32 v11, v11, v162
	v_mul_f32_e32 v12, v12, v162
	v_mul_f32_e32 v13, v13, v162
	v_mul_f32_e32 v14, v14, v162
	v_mul_f32_e32 v15, v15, v162
	v_mul_f32_e32 v16, v16, v162
	v_mul_f32_e32 v17, v17, v162
	v_mul_f32_e32 v18, v18, v162
	v_mul_f32_e32 v19, v19, v162
	v_mul_f32_e32 v20, v20, v162
	v_mul_f32_e32 v21, v21, v162
	v_mul_f32_e32 v22, v22, v162
	v_mul_f32_e32 v23, v23, v162
	v_mul_f32_e32 v24, v24, v162
	v_mul_f32_e32 v25, v25, v162
	v_mul_f32_e32 v26, v26, v162
	v_mul_f32_e32 v27, v27, v162
	v_mul_f32_e32 v28, v28, v162
	v_mul_f32_e32 v29, v29, v162
	v_mul_f32_e32 v30, v30, v162
	v_mul_f32_e32 v31, v31, v162
	v_mul_f32_e32 v32, v32, v162
	v_mul_f32_e32 v33, v33, v162
	v_mul_f32_e32 v1, v1, v162
	v_mov_b32_e32 v162, v49
